# scan step: the six later S^T fragment reads issued together into v220..v243 after the first counted wait; chain waits lgkmcnt(6..0) instead of a read/wait per MFMA pair
# baseline (speedup 1.0000x reference)
.LBB0_469:
	s_waitcnt vmcnt(1)
	v_mov_b64_e32 v[92:93], v[16:17]
	v_mov_b64_e32 v[94:95], v[18:19]
	v_mov_b64_e32 v[88:89], v[20:21]
	v_mov_b64_e32 v[90:91], v[22:23]
	v_mov_b64_e32 v[120:121], v[104:105]
	v_mov_b64_e32 v[118:119], v[102:103]
	v_mov_b32_e32 v116, v100
	ds_read_b128 v[148:151], v200
	ds_read_b128 v[126:129], v200 offset:16384
	ds_read_b128 v[170:173], v201
	ds_read_b128 v[130:133], v201 offset:16384
	ds_read_b128 v[174:177], v202
	ds_read_b128 v[140:143], v202 offset:16384
	ds_read_b128 v[178:181], v203
	ds_read_b128 v[144:147], v203 offset:16384
	ds_read_b128 v[84:87], v208 offset:32768
	ds_read_b128 v[80:83], v208 offset:34816
	ds_read_b128 v[76:79], v209 offset:32768
	ds_read_b128 v[72:75], v209 offset:34816
	ds_read_b128 v[182:185], v124
	ds_read_b128 v[190:193], v124 offset:4352
	s_add_u32 m0, s36, 0x16800
	s_nop 0
	global_load_lds_dwordx4 v194, s[38:39]
	s_add_u32 m0, s36, 0x16c00
	s_nop 0
	global_load_lds_dwordx4 v195, s[38:39]
	s_add_u32 m0, s36, 0x1a800
	s_nop 0
	global_load_lds_dwordx4 v196, s[38:39]
	s_add_u32 m0, s36, 0x1ac00
	s_nop 0
	global_load_lds_dwordx4 v197, s[38:39]
	s_add_u32 m0, s36, 0x1e800
	s_nop 0
	global_load_lds_dwordx4 v198, s[38:39]
	s_add_u32 m0, s36, 0x1ec00
	s_nop 0
	global_load_lds_dwordx4 v199, s[38:39]
	s_add_u32 s38, s38, 0x4000
	s_addc_u32 s39, s39, 0
	v_lshl_add_u64 v[0:1], s[72:73], 0, v[110:111]
	s_mov_b32 s7, 0x23502000
	v_add_co_u32_e32 v0, vcc, s7, v0
	s_nop 1
	v_addc_co_u32_e32 v1, vcc, 0, v1, vcc
	global_load_dwordx4 v[16:19], v[0:1], off
	global_load_dwordx4 v[20:23], v[0:1], off offset:64
	v_lshl_add_u64 v[102:103], s[72:73], 0, v[108:109]
	s_mov_b32 s7, 0x1d504000
	v_add_co_u32_e32 v102, vcc, s7, v102
	s_add_u32 s8, s72, s1
	s_nop 0
	v_addc_co_u32_e32 v103, vcc, 0, v103, vcc
	s_addc_u32 s9, s73, s11
	global_load_dwordx2 v[104:105], v[102:103], off
	s_nop 0
	global_load_dwordx2 v[102:103], v[102:103], off offset:2048
	global_load_dword v100, v137, s[8:9]
	s_waitcnt lgkmcnt(1)
	ds_read_b128 v[220:223], v124 offset:64
	ds_read_b128 v[224:227], v124 offset:4416
	ds_read_b128 v[228:231], v124 offset:128
	ds_read_b128 v[232:235], v124 offset:4480
	ds_read_b128 v[236:239], v124 offset:192
	ds_read_b128 v[240:243], v124 offset:4544
	v_mfma_f32_16x16x32_bf16 v[186:189], v[148:151], v[182:185], 0
	v_lshlrev_b32_e32 v134, 16, v120
	v_and_b32_e32 v135, 0xffff0000, v120
	v_lshlrev_b32_e32 v120, 16, v121
	v_mfma_f32_16x16x32_bf16 v[182:185], v[126:129], v[182:185], 0
	v_and_b32_e32 v121, 0xffff0000, v121
	v_pk_mul_f32 v[70:71], v[70:71], v[116:117] op_sel_hi:[1,0]
	v_pk_mul_f32 v[68:69], v[68:69], v[116:117] op_sel_hi:[1,0]
	s_waitcnt lgkmcnt(6)
	v_mfma_f32_16x16x32_bf16 v[148:151], v[148:151], v[190:193], 0
	v_mul_f32_e64 v58, v58, v116
	v_mul_f32_e64 v59, v59, v116
	v_pk_mul_f32 v[56:57], v[56:57], v[116:117] op_sel_hi:[1,0]
	v_pk_mul_f32 v[62:63], v[62:63], v[116:117] op_sel_hi:[1,0]
	v_mfma_f32_16x16x32_bf16 v[126:129], v[126:129], v[190:193], 0
	s_nop 0
	v_pk_mul_f32 v[60:61], v[60:61], v[116:117] op_sel_hi:[1,0]
	v_pk_mul_f32 v[38:39], v[38:39], v[116:117] op_sel_hi:[1,0]
	s_waitcnt lgkmcnt(5)
	v_mfma_f32_16x16x32_bf16 v[186:189], v[170:173], v[220:223], v[186:189]
	v_mul_f32_e64 v36, v36, v116
	v_mul_f32_e64 v37, v37, v116
	s_add_i32 s6, s6, -1
	s_add_u32 s1, s1, 4
	v_mfma_f32_16x16x32_bf16 v[182:185], v[130:133], v[220:223], v[182:185]
	s_nop 0
	s_addc_u32 s11, s11, 0
	v_lshl_add_u64 v[108:109], v[108:109], 0, s[26:27]
	s_waitcnt lgkmcnt(4)
	v_mfma_f32_16x16x32_bf16 v[126:129], v[130:133], v[224:227], v[126:129]
	s_nop 0
	v_lshl_add_u64 v[110:111], v[110:111], 0, s[14:15]
	v_lshl_add_u64 v[112:113], v[112:113], 0, s[26:27]
	v_mfma_f32_16x16x32_bf16 v[148:151], v[170:173], v[224:227], v[148:151]
	v_lshl_add_u64 v[114:115], v[114:115], 0, s[26:27]
	s_cmp_lg_u32 s6, 0
	s_waitcnt lgkmcnt(3)
	v_mfma_f32_16x16x32_bf16 v[170:173], v[174:177], v[228:231], v[186:189]
	v_mfma_f32_16x16x32_bf16 v[130:133], v[140:143], v[228:231], v[182:185]
	s_nop 2
	s_nop 0
	s_waitcnt lgkmcnt(2)
	v_mfma_f32_16x16x32_bf16 v[126:129], v[140:143], v[232:235], v[126:129]
	s_nop 0
	s_waitcnt lgkmcnt(1)
	v_mfma_f32_16x16x32_bf16 v[170:173], v[178:181], v[236:239], v[170:173]
	v_mfma_f32_16x16x32_bf16 v[130:133], v[144:147], v[236:239], v[130:133]
	s_nop 0
	s_nop 5
	v_pk_add_f32 v[134:135], v[134:135], v[170:171] neg_lo:[0,1] neg_hi:[0,1]
	v_pk_add_f32 v[120:121], v[120:121], v[172:173] neg_lo:[0,1] neg_hi:[0,1]
	v_mfma_f32_16x16x32_bf16 v[148:151], v[174:177], v[232:235], v[148:151]
	v_cvt_pk_bf16_f32 v134, v134, v135
	v_cvt_pk_bf16_f32 v135, v120, v121
	v_lshlrev_b32_e32 v120, 16, v118
	s_waitcnt lgkmcnt(0)
	v_mfma_f32_16x16x32_bf16 v[148:151], v[178:181], v[240:243], v[148:151]
	v_and_b32_e32 v121, 0xffff0000, v118
	v_lshlrev_b32_e32 v118, 16, v119
	v_and_b32_e32 v119, 0xffff0000, v119
	ds_write_b64 v117, v[134:135] offset:8704
	v_mfma_f32_16x16x32_bf16 v[126:129], v[144:147], v[240:243], v[126:129]
	s_nop 2
	v_add_f32_e64 v120, v120, -v148
	v_add_f32_e64 v121, v121, -v149
	v_pk_add_f32 v[118:119], v[118:119], v[150:151] neg_lo:[0,1] neg_hi:[0,1]
	v_cvt_pk_bf16_f32 v120, v120, v121
	v_cvt_pk_bf16_f32 v121, v118, v119
	ds_write_b64 v117, v[120:121] offset:11008
	s_waitcnt lgkmcnt(0)
	s_barrier
	ds_read_b128 v[118:121], v122 offset:8704
	ds_read_b128 v[140:143], v123 offset:13056
	ds_read_b128 v[144:147], v122 offset:8768
	ds_read_b128 v[148:151], v123 offset:13120
	s_waitcnt lgkmcnt(3)
	v_mfma_f32_16x16x32_bf16 v[130:133], v[92:95], v[118:121], v[130:133]
	s_waitcnt lgkmcnt(2)
	v_mfma_f32_16x16x32_bf16 v[92:95], v[92:95], v[140:143], v[126:129]
	v_mfma_f32_16x16x32_bf16 v[68:71], v[84:87], v[118:121], v[68:71]
	v_mfma_f32_16x16x32_bf16 v[56:59], v[80:83], v[118:121], v[56:59]
	s_waitcnt lgkmcnt(1)
	v_mfma_f32_16x16x32_bf16 v[126:129], v[88:91], v[144:147], v[130:133]
	s_waitcnt lgkmcnt(0)
	v_mfma_f32_16x16x32_bf16 v[88:91], v[88:91], v[148:151], v[92:95]
	v_mfma_f32_16x16x32_bf16 v[60:63], v[84:87], v[140:143], v[60:63]
	s_nop 4
	v_cvt_pk_bf16_f32 v92, v126, s0
	s_nop 0
	v_cvt_pk_bf16_f32 v88, v88, s0
	ds_write_b16 v101, v92 offset:13312
	v_mfma_f32_16x16x32_bf16 v[36:39], v[80:83], v[140:143], v[36:39]
	v_cvt_pk_bf16_f32 v92, v127, s0
	ds_write_b16 v101, v88 offset:13344
	v_cvt_pk_bf16_f32 v88, v89, s0
	v_mfma_f32_16x16x32_bf16 v[68:71], v[76:79], v[144:147], v[68:71]
	ds_write_b16 v101, v92 offset:13392
	v_cvt_pk_bf16_f32 v92, v128, s0
	ds_write_b16 v101, v88 offset:13424
	v_mfma_f32_16x16x32_bf16 v[56:59], v[72:75], v[144:147], v[56:59]
	v_cvt_pk_bf16_f32 v88, v90, s0
	ds_write_b16 v101, v92 offset:13472
	v_cvt_pk_bf16_f32 v92, v129, s0
	v_mfma_f32_16x16x32_bf16 v[60:63], v[76:79], v[148:151], v[60:63]
	ds_write_b16 v101, v88 offset:13504
	v_cvt_pk_bf16_f32 v88, v91, s0
	s_nop 1
	v_cvt_pk_bf16_f32 v76, v56, v57
	v_mfma_f32_16x16x32_bf16 v[36:39], v[72:75], v[148:151], v[36:39]
	v_cvt_pk_bf16_f32 v72, v68, v69
	v_cvt_pk_bf16_f32 v73, v70, v71
	v_cvt_pk_bf16_f32 v77, v58, v59
	ds_write_b16 v101, v92 offset:13552
	ds_write_b16 v101, v88 offset:13584
	v_cvt_pk_bf16_f32 v74, v60, v61
	v_cvt_pk_bf16_f32 v75, v62, v63
	ds_write2_b64 v99, v[72:73], v[76:77] offset1:4
	v_cvt_pk_bf16_f32 v76, v36, v37
	v_cvt_pk_bf16_f32 v77, v38, v39
	v_add_u32_e32 v72, 0x1000, v99
	ds_write2_b64 v72, v[74:75], v[76:77] offset0:32 offset1:36
	s_waitcnt lgkmcnt(0)
	s_waitcnt vmcnt(5)
	s_barrier
	ds_read_b128 v[74:77], v97 offset:13312
	v_lshl_add_u64 v[78:79], s[72:73], 0, v[106:107]
	v_lshl_add_u64 v[106:107], v[106:107], 0, s[12:13]
	s_waitcnt lgkmcnt(0)
	global_store_dwordx4 v[78:79], v[74:77], off
	s_waitcnt vmcnt(1)
	v_mov_b64_e32 v[92:93], v[16:17]
	v_mov_b64_e32 v[94:95], v[18:19]
	v_mov_b64_e32 v[88:89], v[20:21]
	v_mov_b64_e32 v[90:91], v[22:23]
	v_mov_b64_e32 v[120:121], v[104:105]
	v_mov_b64_e32 v[118:119], v[102:103]
	v_mov_b32_e32 v116, v100
	ds_read_b128 v[148:151], v204
	ds_read_b128 v[126:129], v204 offset:16384
	ds_read_b128 v[170:173], v205
	ds_read_b128 v[130:133], v205 offset:16384
	ds_read_b128 v[174:177], v206
	ds_read_b128 v[140:143], v206 offset:16384
	ds_read_b128 v[178:181], v207
	ds_read_b128 v[144:147], v207 offset:16384
	ds_read_b128 v[84:87], v210 offset:32768
	ds_read_b128 v[80:83], v210 offset:34816
	ds_read_b128 v[76:79], v211 offset:32768
	ds_read_b128 v[72:75], v211 offset:34816
	ds_read_b128 v[182:185], v124
	ds_read_b128 v[190:193], v124 offset:4352
	s_add_u32 m0, s36, 0x4800
	s_nop 0
	global_load_lds_dwordx4 v194, s[38:39]
	s_add_u32 m0, s36, 0x4c00
	s_nop 0
	global_load_lds_dwordx4 v195, s[38:39]
	s_add_u32 m0, s36, 0x8800
	s_nop 0
	global_load_lds_dwordx4 v196, s[38:39]
	s_add_u32 m0, s36, 0x8c00
	s_nop 0
	global_load_lds_dwordx4 v197, s[38:39]
	s_add_u32 m0, s36, 0xc800
	s_nop 0
	global_load_lds_dwordx4 v198, s[38:39]
	s_add_u32 m0, s36, 0xcc00
	s_nop 0
	global_load_lds_dwordx4 v199, s[38:39]
	s_add_u32 s38, s38, 0x4000
	s_addc_u32 s39, s39, 0
	v_lshl_add_u64 v[0:1], s[72:73], 0, v[110:111]
	s_mov_b32 s7, 0x23502000
	v_add_co_u32_e32 v0, vcc, s7, v0
	s_nop 1
	v_addc_co_u32_e32 v1, vcc, 0, v1, vcc
	global_load_dwordx4 v[16:19], v[0:1], off
	global_load_dwordx4 v[20:23], v[0:1], off offset:64
	v_lshl_add_u64 v[102:103], s[72:73], 0, v[108:109]
	s_mov_b32 s7, 0x1d504000
	v_add_co_u32_e32 v102, vcc, s7, v102
	s_add_u32 s8, s72, s1
	s_nop 0
	v_addc_co_u32_e32 v103, vcc, 0, v103, vcc
	s_addc_u32 s9, s73, s11
	global_load_dwordx2 v[104:105], v[102:103], off
	s_nop 0
	global_load_dwordx2 v[102:103], v[102:103], off offset:2048
	global_load_dword v100, v137, s[8:9]
	s_waitcnt lgkmcnt(1)
	ds_read_b128 v[220:223], v124 offset:64
	ds_read_b128 v[224:227], v124 offset:4416
	ds_read_b128 v[228:231], v124 offset:128
	ds_read_b128 v[232:235], v124 offset:4480
	ds_read_b128 v[236:239], v124 offset:192
	ds_read_b128 v[240:243], v124 offset:4544
	v_mfma_f32_16x16x32_bf16 v[186:189], v[148:151], v[182:185], 0
	v_lshlrev_b32_e32 v134, 16, v120
	v_and_b32_e32 v135, 0xffff0000, v120
	v_lshlrev_b32_e32 v120, 16, v121
	v_mfma_f32_16x16x32_bf16 v[182:185], v[126:129], v[182:185], 0
	v_and_b32_e32 v121, 0xffff0000, v121
	v_pk_mul_f32 v[70:71], v[70:71], v[116:117] op_sel_hi:[1,0]
	v_pk_mul_f32 v[68:69], v[68:69], v[116:117] op_sel_hi:[1,0]
	s_waitcnt lgkmcnt(6)
	v_mfma_f32_16x16x32_bf16 v[148:151], v[148:151], v[190:193], 0
	v_mul_f32_e64 v58, v58, v116
	v_mul_f32_e64 v59, v59, v116
	v_pk_mul_f32 v[56:57], v[56:57], v[116:117] op_sel_hi:[1,0]
	v_pk_mul_f32 v[62:63], v[62:63], v[116:117] op_sel_hi:[1,0]
	v_mfma_f32_16x16x32_bf16 v[126:129], v[126:129], v[190:193], 0
	s_nop 0
	v_pk_mul_f32 v[60:61], v[60:61], v[116:117] op_sel_hi:[1,0]
	v_pk_mul_f32 v[38:39], v[38:39], v[116:117] op_sel_hi:[1,0]
	s_waitcnt lgkmcnt(5)
	v_mfma_f32_16x16x32_bf16 v[186:189], v[170:173], v[220:223], v[186:189]
	v_mul_f32_e64 v36, v36, v116
	v_mul_f32_e64 v37, v37, v116
	s_add_i32 s6, s6, -1
	s_add_u32 s1, s1, 4
	v_mfma_f32_16x16x32_bf16 v[182:185], v[130:133], v[220:223], v[182:185]
	s_nop 0
	s_addc_u32 s11, s11, 0
	v_lshl_add_u64 v[108:109], v[108:109], 0, s[26:27]
	s_waitcnt lgkmcnt(4)
	v_mfma_f32_16x16x32_bf16 v[126:129], v[130:133], v[224:227], v[126:129]
	s_nop 0
	v_lshl_add_u64 v[110:111], v[110:111], 0, s[14:15]
	v_lshl_add_u64 v[112:113], v[112:113], 0, s[26:27]
	v_mfma_f32_16x16x32_bf16 v[148:151], v[170:173], v[224:227], v[148:151]
	v_lshl_add_u64 v[114:115], v[114:115], 0, s[26:27]
	s_cmp_lg_u32 s6, 0
	s_waitcnt lgkmcnt(3)
	v_mfma_f32_16x16x32_bf16 v[170:173], v[174:177], v[228:231], v[186:189]
	v_mfma_f32_16x16x32_bf16 v[130:133], v[140:143], v[228:231], v[182:185]
	s_nop 2
	s_nop 0
	s_waitcnt lgkmcnt(2)
	v_mfma_f32_16x16x32_bf16 v[126:129], v[140:143], v[232:235], v[126:129]
	s_nop 0
	s_waitcnt lgkmcnt(1)
	v_mfma_f32_16x16x32_bf16 v[170:173], v[178:181], v[236:239], v[170:173]
	v_mfma_f32_16x16x32_bf16 v[130:133], v[144:147], v[236:239], v[130:133]
	s_nop 0
	s_nop 5
	v_pk_add_f32 v[134:135], v[134:135], v[170:171] neg_lo:[0,1] neg_hi:[0,1]
	v_pk_add_f32 v[120:121], v[120:121], v[172:173] neg_lo:[0,1] neg_hi:[0,1]
	v_mfma_f32_16x16x32_bf16 v[148:151], v[174:177], v[232:235], v[148:151]
	v_cvt_pk_bf16_f32 v134, v134, v135
	v_cvt_pk_bf16_f32 v135, v120, v121
	v_lshlrev_b32_e32 v120, 16, v118
	s_waitcnt lgkmcnt(0)
	v_mfma_f32_16x16x32_bf16 v[148:151], v[178:181], v[240:243], v[148:151]
	v_and_b32_e32 v121, 0xffff0000, v118
	v_lshlrev_b32_e32 v118, 16, v119
	v_and_b32_e32 v119, 0xffff0000, v119
	ds_write_b64 v117, v[134:135] offset:8704
	v_mfma_f32_16x16x32_bf16 v[126:129], v[144:147], v[240:243], v[126:129]
	s_nop 2
	v_add_f32_e64 v120, v120, -v148
	v_add_f32_e64 v121, v121, -v149
	v_pk_add_f32 v[118:119], v[118:119], v[150:151] neg_lo:[0,1] neg_hi:[0,1]
	v_cvt_pk_bf16_f32 v120, v120, v121
	v_cvt_pk_bf16_f32 v121, v118, v119
	ds_write_b64 v117, v[120:121] offset:11008
	s_waitcnt lgkmcnt(0)
	s_barrier
	ds_read_b128 v[118:121], v122 offset:8704
	ds_read_b128 v[140:143], v123 offset:13056
	ds_read_b128 v[144:147], v122 offset:8768
	ds_read_b128 v[148:151], v123 offset:13120
	s_waitcnt lgkmcnt(3)
	v_mfma_f32_16x16x32_bf16 v[130:133], v[92:95], v[118:121], v[130:133]
	s_waitcnt lgkmcnt(2)
	v_mfma_f32_16x16x32_bf16 v[92:95], v[92:95], v[140:143], v[126:129]
	v_mfma_f32_16x16x32_bf16 v[68:71], v[84:87], v[118:121], v[68:71]
	v_mfma_f32_16x16x32_bf16 v[56:59], v[80:83], v[118:121], v[56:59]
	s_waitcnt lgkmcnt(1)
	v_mfma_f32_16x16x32_bf16 v[126:129], v[88:91], v[144:147], v[130:133]
	s_waitcnt lgkmcnt(0)
	v_mfma_f32_16x16x32_bf16 v[88:91], v[88:91], v[148:151], v[92:95]
	v_mfma_f32_16x16x32_bf16 v[60:63], v[84:87], v[140:143], v[60:63]
	s_nop 4
	v_cvt_pk_bf16_f32 v92, v126, s0
	s_nop 0
	v_cvt_pk_bf16_f32 v88, v88, s0
	ds_write_b16 v101, v92 offset:13312
	v_mfma_f32_16x16x32_bf16 v[36:39], v[80:83], v[140:143], v[36:39]
	v_cvt_pk_bf16_f32 v92, v127, s0
	ds_write_b16 v101, v88 offset:13344
	v_cvt_pk_bf16_f32 v88, v89, s0
	v_mfma_f32_16x16x32_bf16 v[68:71], v[76:79], v[144:147], v[68:71]
	ds_write_b16 v101, v92 offset:13392
	v_cvt_pk_bf16_f32 v92, v128, s0
	ds_write_b16 v101, v88 offset:13424
	v_mfma_f32_16x16x32_bf16 v[56:59], v[72:75], v[144:147], v[56:59]
	v_cvt_pk_bf16_f32 v88, v90, s0
	ds_write_b16 v101, v92 offset:13472
	v_cvt_pk_bf16_f32 v92, v129, s0
	v_mfma_f32_16x16x32_bf16 v[60:63], v[76:79], v[148:151], v[60:63]
	ds_write_b16 v101, v88 offset:13504
	v_cvt_pk_bf16_f32 v88, v91, s0
	s_nop 1
	v_cvt_pk_bf16_f32 v76, v56, v57
	v_mfma_f32_16x16x32_bf16 v[36:39], v[72:75], v[148:151], v[36:39]
	v_cvt_pk_bf16_f32 v72, v68, v69
	v_cvt_pk_bf16_f32 v73, v70, v71
	v_cvt_pk_bf16_f32 v77, v58, v59
	ds_write_b16 v101, v92 offset:13552
	ds_write_b16 v101, v88 offset:13584
	v_cvt_pk_bf16_f32 v74, v60, v61
	v_cvt_pk_bf16_f32 v75, v62, v63
	ds_write2_b64 v99, v[72:73], v[76:77] offset1:4
	v_cvt_pk_bf16_f32 v76, v36, v37
	v_cvt_pk_bf16_f32 v77, v38, v39
	v_add_u32_e32 v72, 0x1000, v99
	ds_write2_b64 v72, v[74:75], v[76:77] offset0:32 offset1:36
	s_waitcnt lgkmcnt(0)
	s_waitcnt vmcnt(5)
	s_barrier
	ds_read_b128 v[74:77], v97 offset:13312
	v_lshl_add_u64 v[78:79], s[72:73], 0, v[106:107]
	v_lshl_add_u64 v[106:107], v[106:107], 0, s[12:13]
	s_waitcnt lgkmcnt(0)
	global_store_dwordx4 v[78:79], v[74:77], off
	s_cbranch_scc1 .LBB0_469
	s_waitcnt vmcnt(1)
	v_mov_b64_e32 v[92:93], v[16:17]
	v_mov_b64_e32 v[94:95], v[18:19]
	v_mov_b64_e32 v[88:89], v[20:21]
	v_mov_b64_e32 v[90:91], v[22:23]
	v_mov_b64_e32 v[120:121], v[104:105]
	v_mov_b64_e32 v[118:119], v[102:103]
	v_mov_b32_e32 v116, v100
	ds_read_b128 v[148:151], v200
	ds_read_b128 v[126:129], v200 offset:16384
	ds_read_b128 v[170:173], v201
	ds_read_b128 v[130:133], v201 offset:16384
	ds_read_b128 v[174:177], v202
	ds_read_b128 v[140:143], v202 offset:16384
	ds_read_b128 v[178:181], v203
	ds_read_b128 v[144:147], v203 offset:16384
	ds_read_b128 v[84:87], v208 offset:32768
	ds_read_b128 v[80:83], v208 offset:34816
	ds_read_b128 v[76:79], v209 offset:32768
	ds_read_b128 v[72:75], v209 offset:34816
	ds_read_b128 v[182:185], v124
	ds_read_b128 v[190:193], v124 offset:4352
	s_add_u32 m0, s36, 0x16800
	s_nop 0
	global_load_lds_dwordx4 v194, s[38:39]
	s_add_u32 m0, s36, 0x16c00
	s_nop 0
	global_load_lds_dwordx4 v195, s[38:39]
	s_add_u32 m0, s36, 0x1a800
	s_nop 0
	global_load_lds_dwordx4 v196, s[38:39]
	s_add_u32 m0, s36, 0x1ac00
	s_nop 0
	global_load_lds_dwordx4 v197, s[38:39]
	s_add_u32 m0, s36, 0x1e800
	s_nop 0
	global_load_lds_dwordx4 v198, s[38:39]
	s_add_u32 m0, s36, 0x1ec00
	s_nop 0
	global_load_lds_dwordx4 v199, s[38:39]
	s_add_u32 s38, s38, 0x4000
	s_addc_u32 s39, s39, 0
	v_lshl_add_u64 v[0:1], s[72:73], 0, v[110:111]
	s_mov_b32 s7, 0x23502000
	v_add_co_u32_e32 v0, vcc, s7, v0
	s_nop 1
	v_addc_co_u32_e32 v1, vcc, 0, v1, vcc
	global_load_dwordx4 v[16:19], v[0:1], off
	global_load_dwordx4 v[20:23], v[0:1], off offset:64
	v_lshl_add_u64 v[102:103], s[72:73], 0, v[108:109]
	s_mov_b32 s7, 0x1d504000
	v_add_co_u32_e32 v102, vcc, s7, v102
	s_add_u32 s8, s72, s1
	s_nop 0
	v_addc_co_u32_e32 v103, vcc, 0, v103, vcc
	s_addc_u32 s9, s73, s11
	global_load_dwordx2 v[104:105], v[102:103], off
	s_nop 0
	global_load_dwordx2 v[102:103], v[102:103], off offset:2048
	global_load_dword v100, v137, s[8:9]
	s_waitcnt lgkmcnt(1)
	ds_read_b128 v[220:223], v124 offset:64
	ds_read_b128 v[224:227], v124 offset:4416
	ds_read_b128 v[228:231], v124 offset:128
	ds_read_b128 v[232:235], v124 offset:4480
	ds_read_b128 v[236:239], v124 offset:192
	ds_read_b128 v[240:243], v124 offset:4544
	v_mfma_f32_16x16x32_bf16 v[186:189], v[148:151], v[182:185], 0
	v_lshlrev_b32_e32 v134, 16, v120
	v_and_b32_e32 v135, 0xffff0000, v120
	v_lshlrev_b32_e32 v120, 16, v121
	v_mfma_f32_16x16x32_bf16 v[182:185], v[126:129], v[182:185], 0
	v_and_b32_e32 v121, 0xffff0000, v121
	v_pk_mul_f32 v[70:71], v[70:71], v[116:117] op_sel_hi:[1,0]
	v_pk_mul_f32 v[68:69], v[68:69], v[116:117] op_sel_hi:[1,0]
	s_waitcnt lgkmcnt(6)
	v_mfma_f32_16x16x32_bf16 v[148:151], v[148:151], v[190:193], 0
	v_mul_f32_e64 v58, v58, v116
	v_mul_f32_e64 v59, v59, v116
	v_pk_mul_f32 v[56:57], v[56:57], v[116:117] op_sel_hi:[1,0]
	v_pk_mul_f32 v[62:63], v[62:63], v[116:117] op_sel_hi:[1,0]
	v_mfma_f32_16x16x32_bf16 v[126:129], v[126:129], v[190:193], 0
	s_nop 0
	v_pk_mul_f32 v[60:61], v[60:61], v[116:117] op_sel_hi:[1,0]
	v_pk_mul_f32 v[38:39], v[38:39], v[116:117] op_sel_hi:[1,0]
	s_waitcnt lgkmcnt(5)
	v_mfma_f32_16x16x32_bf16 v[186:189], v[170:173], v[220:223], v[186:189]
	v_mul_f32_e64 v36, v36, v116
	v_mul_f32_e64 v37, v37, v116
	s_add_i32 s6, s6, -1
	s_add_u32 s1, s1, 4
	v_mfma_f32_16x16x32_bf16 v[182:185], v[130:133], v[220:223], v[182:185]
	s_nop 0
	s_addc_u32 s11, s11, 0
	v_lshl_add_u64 v[108:109], v[108:109], 0, s[26:27]
	s_waitcnt lgkmcnt(4)
	v_mfma_f32_16x16x32_bf16 v[126:129], v[130:133], v[224:227], v[126:129]
	s_nop 0
	v_lshl_add_u64 v[110:111], v[110:111], 0, s[14:15]
	v_lshl_add_u64 v[112:113], v[112:113], 0, s[26:27]
	v_mfma_f32_16x16x32_bf16 v[148:151], v[170:173], v[224:227], v[148:151]
	v_lshl_add_u64 v[114:115], v[114:115], 0, s[26:27]
	s_cmp_lg_u32 s6, 0
	s_waitcnt lgkmcnt(3)
	v_mfma_f32_16x16x32_bf16 v[170:173], v[174:177], v[228:231], v[186:189]
	v_mfma_f32_16x16x32_bf16 v[130:133], v[140:143], v[228:231], v[182:185]
	s_nop 2
	s_nop 0
	s_waitcnt lgkmcnt(2)
	v_mfma_f32_16x16x32_bf16 v[126:129], v[140:143], v[232:235], v[126:129]
	s_nop 0
	s_waitcnt lgkmcnt(1)
	v_mfma_f32_16x16x32_bf16 v[170:173], v[178:181], v[236:239], v[170:173]
	v_mfma_f32_16x16x32_bf16 v[130:133], v[144:147], v[236:239], v[130:133]
	s_nop 0
	s_nop 5
	v_pk_add_f32 v[134:135], v[134:135], v[170:171] neg_lo:[0,1] neg_hi:[0,1]
	v_pk_add_f32 v[120:121], v[120:121], v[172:173] neg_lo:[0,1] neg_hi:[0,1]
	v_mfma_f32_16x16x32_bf16 v[148:151], v[174:177], v[232:235], v[148:151]
	v_cvt_pk_bf16_f32 v134, v134, v135
	v_cvt_pk_bf16_f32 v135, v120, v121
	v_lshlrev_b32_e32 v120, 16, v118
	s_waitcnt lgkmcnt(0)
	v_mfma_f32_16x16x32_bf16 v[148:151], v[178:181], v[240:243], v[148:151]
	v_and_b32_e32 v121, 0xffff0000, v118
	v_lshlrev_b32_e32 v118, 16, v119
	v_and_b32_e32 v119, 0xffff0000, v119
	ds_write_b64 v117, v[134:135] offset:8704
	v_mfma_f32_16x16x32_bf16 v[126:129], v[144:147], v[240:243], v[126:129]
	s_nop 2
	v_add_f32_e64 v120, v120, -v148
	v_add_f32_e64 v121, v121, -v149
	v_pk_add_f32 v[118:119], v[118:119], v[150:151] neg_lo:[0,1] neg_hi:[0,1]
	v_cvt_pk_bf16_f32 v120, v120, v121
	v_cvt_pk_bf16_f32 v121, v118, v119
	ds_write_b64 v117, v[120:121] offset:11008
	s_waitcnt lgkmcnt(0)
	s_barrier
	ds_read_b128 v[118:121], v122 offset:8704
	ds_read_b128 v[140:143], v123 offset:13056
	ds_read_b128 v[144:147], v122 offset:8768
	ds_read_b128 v[148:151], v123 offset:13120
	s_waitcnt lgkmcnt(3)
	v_mfma_f32_16x16x32_bf16 v[130:133], v[92:95], v[118:121], v[130:133]
	s_waitcnt lgkmcnt(2)
	v_mfma_f32_16x16x32_bf16 v[92:95], v[92:95], v[140:143], v[126:129]
	v_mfma_f32_16x16x32_bf16 v[68:71], v[84:87], v[118:121], v[68:71]
	v_mfma_f32_16x16x32_bf16 v[56:59], v[80:83], v[118:121], v[56:59]
	s_waitcnt lgkmcnt(1)
	v_mfma_f32_16x16x32_bf16 v[126:129], v[88:91], v[144:147], v[130:133]
	s_waitcnt lgkmcnt(0)
	v_mfma_f32_16x16x32_bf16 v[88:91], v[88:91], v[148:151], v[92:95]
	v_mfma_f32_16x16x32_bf16 v[60:63], v[84:87], v[140:143], v[60:63]
	s_nop 4
	v_cvt_pk_bf16_f32 v92, v126, s0
	s_nop 0
	v_cvt_pk_bf16_f32 v88, v88, s0
	ds_write_b16 v101, v92 offset:13312
	v_mfma_f32_16x16x32_bf16 v[36:39], v[80:83], v[140:143], v[36:39]
	v_cvt_pk_bf16_f32 v92, v127, s0
	ds_write_b16 v101, v88 offset:13344
	v_cvt_pk_bf16_f32 v88, v89, s0
	v_mfma_f32_16x16x32_bf16 v[68:71], v[76:79], v[144:147], v[68:71]
	ds_write_b16 v101, v92 offset:13392
	v_cvt_pk_bf16_f32 v92, v128, s0
	ds_write_b16 v101, v88 offset:13424
	v_mfma_f32_16x16x32_bf16 v[56:59], v[72:75], v[144:147], v[56:59]
	v_cvt_pk_bf16_f32 v88, v90, s0
	ds_write_b16 v101, v92 offset:13472
	v_cvt_pk_bf16_f32 v92, v129, s0
	v_mfma_f32_16x16x32_bf16 v[60:63], v[76:79], v[148:151], v[60:63]
	ds_write_b16 v101, v88 offset:13504
	v_cvt_pk_bf16_f32 v88, v91, s0
	s_nop 1
	v_cvt_pk_bf16_f32 v76, v56, v57
	v_mfma_f32_16x16x32_bf16 v[36:39], v[72:75], v[148:151], v[36:39]
	v_cvt_pk_bf16_f32 v72, v68, v69
	v_cvt_pk_bf16_f32 v73, v70, v71
	v_cvt_pk_bf16_f32 v77, v58, v59
	ds_write_b16 v101, v92 offset:13552
	ds_write_b16 v101, v88 offset:13584
	v_cvt_pk_bf16_f32 v74, v60, v61
	v_cvt_pk_bf16_f32 v75, v62, v63
	ds_write2_b64 v99, v[72:73], v[76:77] offset1:4
	v_cvt_pk_bf16_f32 v76, v36, v37
	v_cvt_pk_bf16_f32 v77, v38, v39
	v_add_u32_e32 v72, 0x1000, v99
	ds_write2_b64 v72, v[74:75], v[76:77] offset0:32 offset1:36
	s_waitcnt lgkmcnt(0)
	s_waitcnt vmcnt(5)
	s_barrier
	ds_read_b128 v[74:77], v97 offset:13312
	v_lshl_add_u64 v[78:79], s[72:73], 0, v[106:107]
	v_lshl_add_u64 v[106:107], v[106:107], 0, s[12:13]
	s_waitcnt lgkmcnt(0)
	global_store_dwordx4 v[78:79], v[74:77], off
	ds_read_b128 v[52:55], v204
	ds_read_b128 v[64:67], v204 offset:16384
	ds_read_b128 v[44:47], v205
	ds_read_b128 v[48:51], v205 offset:16384
	ds_read_b128 v[32:35], v206
	ds_read_b128 v[40:43], v206 offset:16384
	ds_read_b128 v[24:27], v207
	ds_read_b128 v[28:31], v207 offset:16384
	ds_read_b128 v[12:15], v210 offset:32768
	ds_read_b128 v[8:11], v210 offset:34816
	ds_read_b128 v[4:7], v211 offset:32768
	ds_read_b128 v[0:3], v211 offset:34816
	s_waitcnt lgkmcnt(0)
	ds_read_b128 v[74:77], v124
	ds_read_b128 v[82:85], v124 offset:4352
	s_waitcnt vmcnt(1)
	v_pk_mul_f32 v[38:39], v[100:101], v[38:39] op_sel_hi:[0,1]
	v_pk_mul_f32 v[36:37], v[100:101], v[36:37] op_sel_hi:[0,1]
	s_mov_b32 s1, s52
	s_waitcnt lgkmcnt(1)
	v_mfma_f32_16x16x32_bf16 v[78:81], v[52:55], v[74:77], 0
	v_mfma_f32_16x16x32_bf16 v[74:77], v[64:67], v[74:77], 0
	s_waitcnt lgkmcnt(0)
	v_mfma_f32_16x16x32_bf16 v[52:55], v[52:55], v[82:85], 0
	v_mfma_f32_16x16x32_bf16 v[64:67], v[64:67], v[82:85], 0
	ds_read_b128 v[82:85], v124 offset:64
	s_waitcnt lgkmcnt(0)
	v_mfma_f32_16x16x32_bf16 v[78:81], v[44:47], v[82:85], v[78:81]
	v_mfma_f32_16x16x32_bf16 v[74:77], v[48:51], v[82:85], v[74:77]
	ds_read_b128 v[82:85], v124 offset:4416
	s_waitcnt lgkmcnt(0)
	v_mfma_f32_16x16x32_bf16 v[44:47], v[44:47], v[82:85], v[52:55]
	s_nop 2
	ds_read_b128 v[52:55], v124 offset:128
	v_mfma_f32_16x16x32_bf16 v[48:51], v[48:51], v[82:85], v[64:67]
	s_waitcnt lgkmcnt(0)
	v_mfma_f32_16x16x32_bf16 v[64:67], v[32:35], v[52:55], v[78:81]
	v_mfma_f32_16x16x32_bf16 v[52:55], v[40:43], v[52:55], v[74:77]
	s_nop 2
	ds_read_b128 v[74:77], v124 offset:4480
	s_waitcnt lgkmcnt(0)
	v_mfma_f32_16x16x32_bf16 v[32:35], v[32:35], v[74:77], v[44:47]
	s_nop 2
	ds_read_b128 v[44:47], v124 offset:192
	v_mfma_f32_16x16x32_bf16 v[40:43], v[40:43], v[74:77], v[48:51]
	s_waitcnt lgkmcnt(0)
	v_mfma_f32_16x16x32_bf16 v[48:51], v[24:27], v[44:47], v[64:67]
	v_mfma_f32_16x16x32_bf16 v[44:47], v[28:31], v[44:47], v[52:55]
	s_nop 2
	ds_read_b128 v[52:55], v124 offset:4544
	s_waitcnt lgkmcnt(0)
	v_mfma_f32_16x16x32_bf16 v[24:27], v[24:27], v[52:55], v[32:35]
	s_nop 2
	v_lshlrev_b32_e32 v32, 16, v104
	v_and_b32_e32 v33, 0xffff0000, v104
	v_lshlrev_b32_e32 v34, 16, v105
	v_and_b32_e32 v35, 0xffff0000, v105
	v_pk_add_f32 v[32:33], v[32:33], v[48:49] neg_lo:[0,1] neg_hi:[0,1]
	v_pk_add_f32 v[34:35], v[34:35], v[50:51] neg_lo:[0,1] neg_hi:[0,1]
	v_cvt_pk_bf16_f32 v32, v32, v33
	v_cvt_pk_bf16_f32 v33, v34, v35
	ds_write_b64 v117, v[32:33] offset:8704
	v_lshlrev_b32_e32 v32, 16, v102
	v_and_b32_e32 v33, 0xffff0000, v102
	v_pk_add_f32 v[24:25], v[32:33], v[24:25] neg_lo:[0,1] neg_hi:[0,1]
	v_lshlrev_b32_e32 v32, 16, v103
	v_and_b32_e32 v33, 0xffff0000, v103
	v_pk_add_f32 v[26:27], v[32:33], v[26:27] neg_lo:[0,1] neg_hi:[0,1]
	v_cvt_pk_bf16_f32 v24, v24, v25
	v_cvt_pk_bf16_f32 v25, v26, v27
	ds_write_b64 v117, v[24:25] offset:11008
	v_mfma_f32_16x16x32_bf16 v[28:31], v[28:31], v[52:55], v[40:43]
	s_waitcnt lgkmcnt(0)
	s_barrier
	ds_read_b128 v[24:27], v122 offset:8704
	ds_read_b128 v[32:35], v123 offset:13056
	ds_read_b128 v[40:43], v122 offset:8768
	ds_read_b128 v[48:51], v123 offset:13120
	s_waitcnt lgkmcnt(3)
	v_mfma_f32_16x16x32_bf16 v[44:47], v[16:19], v[24:27], v[44:47]
	s_waitcnt lgkmcnt(2)
	v_mfma_f32_16x16x32_bf16 v[16:19], v[16:19], v[32:35], v[28:31]
	s_waitcnt lgkmcnt(1)
	v_mfma_f32_16x16x32_bf16 v[28:31], v[20:23], v[40:43], v[44:47]
	s_waitcnt lgkmcnt(0)
	v_mfma_f32_16x16x32_bf16 v[16:19], v[20:23], v[48:51], v[16:19]
	v_mul_f32_e64 v22, v100, v62
	v_mul_f32_e64 v23, v100, v63
	s_nop 3
	v_cvt_pk_bf16_f32 v20, v28, s0
	ds_write_b16 v101, v20 offset:13312
	v_cvt_pk_bf16_f32 v20, v29, s0
	ds_write_b16 v101, v20 offset:13392
	v_cvt_pk_bf16_f32 v16, v16, s0
	ds_write_b16 v101, v16 offset:13344
	v_cvt_pk_bf16_f32 v16, v17, s0
	v_cvt_pk_bf16_f32 v20, v30, s0
	ds_write_b16 v101, v16 offset:13424
	v_cvt_pk_bf16_f32 v16, v18, s0
	ds_write_b16 v101, v20 offset:13472
	v_cvt_pk_bf16_f32 v20, v31, s0
	ds_write_b16 v101, v16 offset:13504
	v_cvt_pk_bf16_f32 v16, v19, s0
	ds_write_b16 v101, v20 offset:13552
	ds_write_b16 v101, v16 offset:13584
	v_pk_mul_f32 v[18:19], v[100:101], v[70:71] op_sel_hi:[0,1]
	v_pk_mul_f32 v[16:17], v[100:101], v[68:69] op_sel_hi:[0,1]
	v_pk_mul_f32 v[20:21], v[100:101], v[60:61] op_sel_hi:[0,1]
	v_pk_mul_f32 v[30:31], v[100:101], v[58:59] op_sel_hi:[0,1]
	v_pk_mul_f32 v[28:29], v[100:101], v[56:57] op_sel_hi:[0,1]
	v_mfma_f32_16x16x32_bf16 v[16:19], v[12:15], v[24:27], v[16:19]
	v_mfma_f32_16x16x32_bf16 v[12:15], v[12:15], v[32:35], v[20:23]
	v_mfma_f32_16x16x32_bf16 v[20:23], v[8:11], v[24:27], v[28:31]
	v_mfma_f32_16x16x32_bf16 v[8:11], v[8:11], v[32:35], v[36:39]
	v_mfma_f32_16x16x32_bf16 v[16:19], v[4:7], v[40:43], v[16:19]
	v_mfma_f32_16x16x32_bf16 v[4:7], v[4:7], v[48:51], v[12:15]
	v_mfma_f32_16x16x32_bf16 v[12:15], v[0:3], v[40:43], v[20:23]
	v_mfma_f32_16x16x32_bf16 v[0:3], v[0:3], v[48:51], v[8:11]
	s_nop 5
	v_cvt_pk_bf16_f32 v4, v4, v5
	v_cvt_pk_bf16_f32 v5, v6, v7
	v_cvt_pk_bf16_f32 v6, v12, v13
	v_cvt_pk_bf16_f32 v8, v16, v17
	v_cvt_pk_bf16_f32 v9, v18, v19
	v_cvt_pk_bf16_f32 v7, v14, v15
	v_cvt_pk_bf16_f32 v0, v0, v1
	v_cvt_pk_bf16_f32 v1, v2, v3
	ds_write2_b64 v99, v[8:9], v[6:7] offset1:4
	ds_write2_b64 v72, v[4:5], v[0:1] offset0:32 offset1:36
	s_waitcnt lgkmcnt(0)
	s_barrier
	v_lshl_or_b32 v4, v98, 11, s4
	v_mov_b32_e32 v5, s5
	v_readlane_b32 s4, v254, 36
	ds_read_b128 v[0:3], v97 offset:13312
	v_readlane_b32 s5, v254, 37
	v_mov_b32_e32 v97, v137
	s_nop 0
	v_lshl_add_u64 v[4:5], s[4:5], 0, v[4:5]
	v_lshl_add_u64 v[4:5], v[4:5], 0, s[0:1]
	s_lshl_b32 s0, s10, 6
	v_lshl_add_u64 v[4:5], v[4:5], 0, s[0:1]
	v_lshl_add_u64 v[4:5], v[4:5], 0, v[96:97]
	s_waitcnt lgkmcnt(0)
	global_store_dwordx4 v[4:5], v[0:3], off
